# plus: sliding-window head loop with 3-deep LDS fragment prefetch
# speedup vs baseline: 1.0021x; 1.0021x over previous
.LBB0_189:
	ds_read_b128 v[50:53], v117
	ds_read_b128 v[54:57], v117 offset:64
	ds_read_b128 v[58:61], v118
	v_readlane_b32 s4, v244, 10
	s_xor_b64 s[2:3], s[2:3], -1
	s_lshl_b64 s[94:95], s[90:91], 2
	v_readlane_b32 s16, v244, 22
	v_readlane_b32 s17, v244, 23
	s_add_u32 s94, s16, s94
	s_addc_u32 s95, s17, s95
	global_load_dword v99, v3, s[94:95]
	ds_read_b128 v[146:149], v118 offset:64
	s_waitcnt lgkmcnt(3)
	v_mfma_f32_16x16x32_bf16 v[134:137], v[50:53], v[72:75], 0
	v_readlane_b32 s6, v244, 12
	v_readlane_b32 s7, v244, 13
	s_mov_b32 s4, 0xf149f2ca
	s_waitcnt lgkmcnt(1)
	v_mfma_f32_16x16x32_bf16 v[142:145], v[58:61], v[72:75], 0
	v_readlane_b32 s6, v243, 12
	v_mov_b32_e32 v100, s4
	v_readlane_b32 s7, v243, 13
	v_mfma_f32_16x16x32_bf16 v[134:137], v[54:57], v[68:71], v[134:137]
	ds_read_b128 v[50:53], v119
	ds_read_b128 v[58:61], v119 offset:64
	v_mov_b32_e32 v178, s4
	v_mov_b32_e32 v216, s4
	s_waitcnt lgkmcnt(2)
	v_mfma_f32_16x16x32_bf16 v[142:145], v[146:149], v[68:71], v[142:145]
	ds_read_b128 v[54:57], v120
	ds_read_b128 v[154:157], v120 offset:64
	ds_read_b128 v[158:161], v121
	ds_read_b128 v[162:165], v121 offset:64
	v_cndmask_b32_e64 v100, v100, v134, s[6:7]
	s_waitcnt lgkmcnt(5)
	v_mfma_f32_16x16x32_bf16 v[138:141], v[50:53], v[72:75], 0
	v_readlane_b32 s6, v243, 14
	v_readlane_b32 s7, v243, 15
	v_mov_b32_e32 v218, s4
	s_waitcnt lgkmcnt(1)
	v_mfma_f32_16x16x32_bf16 v[158:161], v[158:161], v[72:75], 0
	v_mov_b32_e32 v220, s4
	v_mov_b32_e32 v222, s4
	v_readlane_b32 s5, v244, 11
	v_mfma_f32_16x16x32_bf16 v[138:141], v[58:61], v[68:71], v[138:141]
	ds_read_b128 v[50:53], v122
	ds_read_b128 v[58:61], v122 offset:64
	ds_read_b128 v[170:173], v123
	ds_read_b128 v[174:177], v123 offset:64
	ds_read_b128 v[196:199], v124
	ds_read_b128 v[200:203], v124 offset:64
	ds_read_b128 v[204:207], v125
	ds_read_b128 v[208:211], v125 offset:64
	v_readlane_b32 s8, v244, 14
	s_waitcnt lgkmcnt(8)
	v_mfma_f32_16x16x32_bf16 v[158:161], v[162:165], v[68:71], v[158:161]
	v_cndmask_b32_e64 v163, v184, v135, s[6:7]
	v_readlane_b32 s6, v243, 16
	v_readlane_b32 s7, v243, 17
	s_waitcnt lgkmcnt(7)
	v_mfma_f32_16x16x32_bf16 v[146:149], v[50:53], v[72:75], 0
	v_mov_b32_e32 v162, s4
	v_cndmask_b32_e64 v165, v184, v136, s[6:7]
	v_readlane_b32 s6, v243, 18
	v_readlane_b32 s7, v243, 19
	s_waitcnt lgkmcnt(6)
	v_mfma_f32_16x16x32_bf16 v[146:149], v[58:61], v[68:71], v[146:149]
	v_cndmask_b32_e64 v158, v162, v158, s[36:37]
	v_cndmask_b32_e64 v166, v184, v137, s[6:7]
	v_readlane_b32 s6, v243, 20
	v_readlane_b32 s7, v243, 21
	v_mfma_f32_16x16x32_bf16 v[150:153], v[54:57], v[72:75], 0
	v_cndmask_b32_e64 v159, v184, v159, s[38:39]
	v_cndmask_b32_e64 v167, v178, v142, s[6:7]
	v_readlane_b32 s6, v243, 22
	v_readlane_b32 s7, v243, 23
	v_mfma_f32_16x16x32_bf16 v[150:153], v[154:157], v[68:71], v[150:153]
	ds_read_b128 v[50:53], v126
	ds_read_b128 v[58:61], v126 offset:64
	v_cndmask_b32_e64 v168, v184, v143, s[6:7]
	v_readlane_b32 s6, v243, 24
	v_readlane_b32 s7, v243, 25
	s_waitcnt lgkmcnt(7)
	v_mfma_f32_16x16x32_bf16 v[134:137], v[170:173], v[72:75], 0
	v_cndmask_b32_e64 v171, v216, v138, s[0:1]
	v_cndmask_b32_e64 v169, v184, v144, s[6:7]
	v_readlane_b32 s6, v243, 26
	v_readlane_b32 s7, v243, 27
	s_waitcnt lgkmcnt(6)
	v_mfma_f32_16x16x32_bf16 v[134:137], v[174:177], v[68:71], v[134:137]
	v_cndmask_b32_e64 v172, v184, v139, s[20:21]
	v_cndmask_b32_e64 v170, v184, v145, s[6:7]
	v_cndmask_b32_e64 v173, v184, v140, s[22:23]
	s_waitcnt lgkmcnt(5)
	v_mfma_f32_16x16x32_bf16 v[142:145], v[196:199], v[72:75], 0
	v_cndmask_b32_e64 v174, v184, v141, s[24:25]
	v_cndmask_b32_e64 v150, v218, v150, s[26:27]
	v_cndmask_b32_e64 v151, v184, v151, s[28:29]
	s_waitcnt lgkmcnt(4)
	v_mfma_f32_16x16x32_bf16 v[138:141], v[200:203], v[68:71], v[142:145]
	v_cndmask_b32_e64 v152, v184, v152, s[30:31]
	v_cndmask_b32_e64 v153, v184, v153, s[34:35]
	v_mov_b32_e32 v164, s4
	s_waitcnt lgkmcnt(3)
	v_mfma_f32_16x16x32_bf16 v[142:145], v[204:207], v[72:75], 0
	v_cndmask_b32_e64 v160, v184, v160, s[40:41]
	v_cndmask_b32_e64 v161, v184, v161, s[42:43]
	v_cndmask_b32_e64 v146, v164, v146, s[44:45]
	s_waitcnt lgkmcnt(1)
	v_mfma_f32_16x16x32_bf16 v[72:75], v[50:53], v[72:75], 0
	v_cndmask_b32_e64 v147, v184, v147, s[46:47]
	v_cndmask_b32_e64 v148, v184, v148, s[48:49]
	v_cndmask_b32_e64 v149, v184, v149, s[50:51]
	v_mfma_f32_16x16x32_bf16 v[142:145], v[208:211], v[68:71], v[142:145]
	v_add_u32_e32 v62, 0xb000, v127
	ds_read_b128 v[54:57], v62 offset:256
	v_add_u32_e32 v63, 0x9000, v127
	ds_read_b128 v[50:53], v63
	v_cndmask_b32_e64 v134, v220, v134, s[52:53]
	v_cndmask_b32_e64 v135, v184, v135, s[54:55]
	v_readlane_b32 s9, v244, 15
	s_waitcnt lgkmcnt(2)
	v_mfma_f32_16x16x32_bf16 v[68:71], v[58:61], v[68:71], v[72:75]
	v_add_u32_e32 v90, 0xd000, v127
	ds_read_b128 v[58:61], v90 offset:512
	v_readlane_b32 s10, v244, 16
	s_nop 1
	v_cndmask_b32_e64 v154, v184, v143, s[70:71]
	v_cndmask_b32_e64 v155, v184, v144, s[72:73]
	s_waitcnt vmcnt(0)
	v_mul_f32_e32 v72, 0x3fb8aa3b, v99
	v_max3_f32 v72, v72, v100, v163
	v_max3_f32 v72, v72, v165, v166
	v_max3_f32 v72, v72, v167, v168
	v_max3_f32 v72, v72, v169, v170
	v_max3_f32 v72, v72, v171, v172
	v_max3_f32 v72, v72, v173, v174
	v_max3_f32 v72, v72, v150, v151
	v_max3_f32 v72, v72, v152, v153
	v_max3_f32 v72, v72, v158, v159
	v_max3_f32 v72, v72, v160, v161
	v_max3_f32 v72, v72, v146, v147
	v_max3_f32 v72, v72, v148, v149
	v_cndmask_b32_e64 v73, v184, v136, s[56:57]
	v_cndmask_b32_e64 v74, v184, v137, s[58:59]
	v_max3_f32 v72, v72, v134, v135
	v_cndmask_b32_e64 v75, v222, v138, s[60:61]
	v_cndmask_b32_e64 v136, v184, v139, s[62:63]
	v_max3_f32 v72, v72, v73, v74
	v_max3_f32 v72, v72, v75, v136
	v_cndmask_b32_e64 v137, v184, v140, s[64:65]
	v_cndmask_b32_e64 v138, v184, v141, s[66:67]
	v_max3_f32 v139, v72, v137, v138
	v_mov_b32_e32 v72, s4
	v_cndmask_b32_e64 v140, v72, v142, s[68:69]
	v_max3_f32 v72, v139, v140, v154
	v_cndmask_b32_e64 v162, v184, v145, s[74:75]
	v_max3_f32 v139, v72, v155, v162
	v_mov_b32_e32 v72, s4
	v_cndmask_b32_e64 v164, v72, v68, s[76:77]
	v_cndmask_b32_e64 v175, v184, v69, s[78:79]
	v_max3_f32 v68, v139, v164, v175
	v_cndmask_b32_e64 v176, v184, v70, s[80:81]
	v_cndmask_b32_e64 v177, v184, v71, s[82:83]
	v_max3_f32 v68, v68, v176, v177
	v_mov_b32_e32 v69, v68
	s_nop 1
	v_permlane16_swap_b32 v69, v68
	s_mov_b32 s4, 0x3fb8aa3b
	v_readlane_b32 s11, v244, 17
	v_readlane_b32 s12, v244, 18
	v_readlane_b32 s13, v244, 19
	v_max_f32_e32 v69, v69, v69
	v_max_f32_e32 v68, v68, v69
	v_mov_b32_e32 v69, v68
	s_nop 1
	v_permlane32_swap_b32 v69, v68
	v_readlane_b32 s14, v244, 20
	v_readlane_b32 s15, v244, 21
	v_readlane_b32 s18, v244, 24
	v_readlane_b32 s19, v244, 25
	v_max_f32_e32 v69, v69, v69
	v_max_f32_e32 v178, v68, v69
	v_sub_f32_e32 v68, v100, v178
	v_exp_f32_e32 v72, v68
	v_sub_f32_e32 v68, v163, v178
	v_exp_f32_e32 v100, v68
	v_sub_f32_e32 v69, v165, v178
	v_exp_f32_e32 v139, v69
	v_sub_f32_e32 v69, v166, v178
	v_exp_f32_e32 v141, v69
	v_sub_f32_e32 v69, v167, v178
	v_add_f32_e32 v68, 0, v72
	v_exp_f32_e32 v142, v69
	v_sub_f32_e32 v69, v168, v178
	v_add_f32_e32 v68, v100, v68
	v_exp_f32_e32 v143, v69
	v_sub_f32_e32 v69, v169, v178
	v_add_f32_e32 v68, v139, v68
	v_exp_f32_e32 v144, v69
	v_sub_f32_e32 v69, v170, v178
	v_add_f32_e32 v68, v141, v68
	v_exp_f32_e32 v145, v69
	v_sub_f32_e32 v69, v171, v178
	v_add_f32_e32 v68, v142, v68
	v_exp_f32_e32 v156, v69
	v_sub_f32_e32 v69, v172, v178
	v_add_f32_e32 v68, v143, v68
	v_exp_f32_e32 v157, v69
	v_sub_f32_e32 v69, v173, v178
	v_add_f32_e32 v68, v144, v68
	v_exp_f32_e32 v163, v69
	v_sub_f32_e32 v69, v174, v178
	v_add_f32_e32 v68, v145, v68
	v_exp_f32_e32 v165, v69
	v_sub_f32_e32 v69, v150, v178
	v_add_f32_e32 v68, v156, v68
	v_exp_f32_e32 v166, v69
	v_sub_f32_e32 v69, v151, v178
	v_add_f32_e32 v68, v157, v68
	v_exp_f32_e32 v167, v69
	v_sub_f32_e32 v69, v152, v178
	v_add_f32_e32 v68, v163, v68
	v_exp_f32_e32 v168, v69
	v_sub_f32_e32 v69, v153, v178
	v_add_f32_e32 v68, v165, v68
	v_exp_f32_e32 v169, v69
	v_sub_f32_e32 v69, v158, v178
	v_add_f32_e32 v68, v166, v68
	v_exp_f32_e32 v158, v69
	v_sub_f32_e32 v69, v159, v178
	v_add_f32_e32 v68, v167, v68
	v_exp_f32_e32 v159, v69
	v_sub_f32_e32 v69, v160, v178
	v_add_f32_e32 v68, v168, v68
	v_exp_f32_e32 v160, v69
	v_sub_f32_e32 v69, v161, v178
	v_add_f32_e32 v68, v169, v68
	v_exp_f32_e32 v161, v69
	v_sub_f32_e32 v69, v146, v178
	v_add_f32_e32 v68, v158, v68
	v_exp_f32_e32 v170, v69
	v_sub_f32_e32 v69, v147, v178
	v_add_f32_e32 v68, v159, v68
	v_exp_f32_e32 v171, v69
	v_sub_f32_e32 v69, v148, v178
	v_add_f32_e32 v68, v160, v68
	v_exp_f32_e32 v172, v69
	v_sub_f32_e32 v69, v149, v178
	v_add_f32_e32 v68, v161, v68
	v_exp_f32_e32 v173, v69
	v_sub_f32_e32 v69, v134, v178
	v_add_f32_e32 v68, v170, v68
	v_exp_f32_e32 v174, v69
	v_sub_f32_e32 v69, v135, v178
	v_add_f32_e32 v68, v171, v68
	v_exp_f32_e32 v179, v69
	v_sub_f32_e32 v69, v73, v178
	v_add_f32_e32 v68, v172, v68
	v_exp_f32_e32 v195, v69
	v_sub_f32_e32 v69, v74, v178
	v_add_f32_e32 v68, v173, v68
	v_exp_f32_e32 v196, v69
	v_sub_f32_e32 v69, v75, v178
	v_add_f32_e32 v68, v174, v68
	v_exp_f32_e32 v197, v69
	v_sub_f32_e32 v69, v136, v178
	v_add_f32_e32 v68, v179, v68
	v_exp_f32_e32 v198, v69
	v_add_f32_e32 v68, v195, v68
	v_add_f32_e32 v68, v196, v68
	v_add_f32_e32 v68, v197, v68
	v_add_f32_e32 v146, v198, v68
	v_sub_f32_e32 v68, v137, v178
	v_exp_f32_e32 v199, v68
	v_sub_f32_e32 v68, v138, v178
	v_add_u32_e32 v74, 0xb000, v127
	v_exp_f32_e32 v200, v68
	v_add_u32_e32 v68, 0x9000, v127
	v_cvt_pk_bf16_f32 v72, v72, v100
	v_cvt_pk_bf16_f32 v74, v142, v143
	v_add_u32_e32 v100, 0xd000, v127
	v_add_u32_e32 v142, 0xf000, v127
	v_sub_f32_e32 v147, v140, v178
	v_cvt_pk_bf16_f32 v73, v139, v141
	v_cvt_pk_bf16_f32 v75, v144, v145
	ds_read_b128 v[142:145], v142 offset:768
	s_waitcnt lgkmcnt(2)
	v_mfma_f32_16x16x32_bf16 v[68:71], v[50:53], v[72:75], 0
	v_add_u32_e32 v91, 0x9000, v130
	ds_read_b128 v[50:53], v91
	v_exp_f32_e32 v100, v147
	v_add_f32_e32 v146, v199, v146
	v_add_f32_e32 v146, v200, v146
	v_mfma_f32_16x16x32_bf16 v[134:137], v[54:57], v[72:75], 0
	v_add_f32_e32 v201, v100, v146
	v_sub_f32_e32 v146, v154, v178
	v_add_u32_e32 v148, 0xb000, v130
	s_waitcnt lgkmcnt(2)
	v_mfma_f32_16x16x32_bf16 v[138:141], v[58:61], v[72:75], 0
	ds_read_b128 v[54:57], v148 offset:256
	v_exp_f32_e32 v202, v146
	v_cvt_pk_bf16_f32 v146, v156, v157
	v_cvt_pk_bf16_f32 v147, v163, v165
	s_waitcnt lgkmcnt(2)
	v_mfma_f32_16x16x32_bf16 v[72:75], v[142:145], v[72:75], 0
	v_add_u32_e32 v94, 0xf000, v130
	ds_read_b128 v[58:61], v94 offset:768
	v_add_u32_e32 v142, 0x9000, v130
	v_cvt_pk_bf16_f32 v148, v166, v167
	v_cvt_pk_bf16_f32 v149, v168, v169
	v_add_u32_e32 v154, 0xd000, v130
	s_waitcnt lgkmcnt(2)
	v_mfma_f32_16x16x32_bf16 v[68:71], v[50:53], v[146:149], v[68:71]
	ds_read_b128 v[50:53], v154 offset:512
	v_add_u32_e32 v142, 0xf000, v130
	v_sub_f32_e32 v203, v155, v178
	s_waitcnt lgkmcnt(1)
	v_mfma_f32_16x16x32_bf16 v[72:75], v[58:61], v[146:149], v[72:75]
	v_add_u32_e32 v142, 0x9000, v131
	ds_read_b128 v[58:61], v142
	v_exp_f32_e32 v163, v203
	v_mfma_f32_16x16x32_bf16 v[134:137], v[54:57], v[146:149], v[134:137]
	v_add_u32_e32 v95, 0xb000, v131
	ds_read_b128 v[54:57], v95 offset:256
	v_sub_f32_e32 v150, v162, v178
	v_exp_f32_e32 v162, v150
	v_add_f32_e32 v150, v202, v201
	s_waitcnt lgkmcnt(2)
	v_mfma_f32_16x16x32_bf16 v[138:141], v[50:53], v[146:149], v[138:141]
	v_add_u32_e32 v129, 0xf000, v131
	ds_read_b128 v[50:53], v129 offset:768
	v_add_f32_e32 v150, v163, v150
	v_add_u32_e32 v148, 0xb000, v131
	v_add_f32_e32 v165, v162, v150
	v_cvt_pk_bf16_f32 v146, v158, v159
	v_cvt_pk_bf16_f32 v147, v160, v161
	v_cvt_pk_bf16_f32 v148, v170, v171
	v_cvt_pk_bf16_f32 v149, v172, v173
	v_add_u32_e32 v154, 0xd000, v131
	s_waitcnt lgkmcnt(2)
	v_mfma_f32_16x16x32_bf16 v[68:71], v[58:61], v[146:149], v[68:71]
	ds_read_b128 v[58:61], v154 offset:512
	v_add_u32_e32 v142, 0xf000, v131
	s_waitcnt lgkmcnt(1)
	s_nop 0
	v_mfma_f32_16x16x32_bf16 v[72:75], v[50:53], v[146:149], v[72:75]
	v_add_u32_e32 v142, 0x9000, v132
	ds_read_b128 v[50:53], v142
	v_sub_f32_e32 v164, v164, v178
	v_mfma_f32_16x16x32_bf16 v[134:137], v[54:57], v[146:149], v[134:137]
	v_add_u32_e32 v221, 0xb000, v132
	ds_read_b128 v[54:57], v221 offset:256
	v_sub_f32_e32 v150, v175, v178
	v_exp_f32_e32 v160, v150
	v_sub_f32_e32 v150, v176, v178
	s_waitcnt lgkmcnt(2)
	v_mfma_f32_16x16x32_bf16 v[138:141], v[58:61], v[146:149], v[138:141]
	v_add_u32_e32 v223, 0xd000, v132
	ds_read_b128 v[58:61], v223 offset:512
	v_add_u32_e32 v148, 0xb000, v132
	v_exp_f32_e32 v161, v150
	v_exp_f32_e32 v158, v164
	v_sub_f32_e32 v164, v177, v178
	v_exp_f32_e32 v164, v164
	v_cvt_pk_bf16_f32 v146, v174, v179
	v_add_f32_e32 v159, v158, v165
	v_cvt_pk_bf16_f32 v147, v195, v196
	v_cvt_pk_bf16_f32 v148, v197, v198
	v_cvt_pk_bf16_f32 v149, v199, v200
	v_add_u32_e32 v154, 0xd000, v132
	s_waitcnt lgkmcnt(2)
	v_mfma_f32_16x16x32_bf16 v[68:71], v[50:53], v[146:149], v[68:71]
	v_add_u32_e32 v48, 0xf000, v132
	ds_read_b128 v[50:53], v48 offset:768
	v_add_f32_e32 v142, v160, v159
	v_add_f32_e32 v142, v161, v142
	s_waitcnt lgkmcnt(2)
	v_mfma_f32_16x16x32_bf16 v[134:137], v[54:57], v[146:149], v[134:137]
	v_add_u32_e32 v62, 0x9000, v133
	ds_read_b128 v[54:57], v62
	v_add_f32_e32 v150, v164, v142
	v_add_u32_e32 v142, 0xf000, v132
	s_nop 0
	v_mov_b32_e32 v151, v150
	s_nop 1
	v_permlane16_swap_b32 v151, v150
	s_waitcnt lgkmcnt(1)
	v_mfma_f32_16x16x32_bf16 v[72:75], v[50:53], v[146:149], v[72:75]
	v_add_u32_e32 v142, 0x9000, v133
	v_add_f32_e32 v159, v150, v151
	v_mfma_f32_16x16x32_bf16 v[138:141], v[58:61], v[146:149], v[138:141]
	v_add_u32_e32 v63, 0xb000, v133
	ds_read_b128 v[50:53], v63 offset:256
	v_add_u32_e32 v90, 0xd000, v133
	ds_read_b128 v[58:61], v90 offset:512
	v_mov_b32_e32 v165, v159
	s_nop 1
	v_permlane32_swap_b32 v165, v159
	v_cvt_pk_bf16_f32 v146, v100, v202
	v_add_u32_e32 v100, 0xb000, v133
	s_nop 0
	v_add_u32_e32 v100, 0xd000, v133
	v_fma_f32 v99, v99, s4, -v178
	s_nop 0
	v_add_u32_e32 v100, 0xf000, v133
	v_exp_f32_e32 v99, v99
	v_cvt_pk_bf16_f32 v147, v163, v162
	v_cvt_pk_bf16_f32 v148, v158, v160
	v_cvt_pk_bf16_f32 v149, v161, v164
	v_writelane_b32 v244, s90, 62
	s_waitcnt lgkmcnt(2)
	v_mfma_f32_16x16x32_bf16 v[68:71], v[54:57], v[146:149], v[68:71]
	ds_read_b128 v[54:57], v100 offset:768
	v_add_f32_e32 v100, v159, v165
	v_add_f32_e32 v99, v99, v100
	v_rcp_f32_e32 v100, v99
	s_waitcnt lgkmcnt(2)
	v_mfma_f32_16x16x32_bf16 v[134:137], v[50:53], v[146:149], v[134:137]
	v_lshl_add_u32 v99, s90, 7, v109
	s_mov_b32 s16, 0xf149f2ca
	s_nop 0
	v_pk_mul_f32 v[70:71], v[70:71], v[100:101] op_sel_hi:[1,0]
	s_waitcnt lgkmcnt(1)
	v_mfma_f32_16x16x32_bf16 v[138:141], v[58:61], v[146:149], v[138:141]
	v_mul_f32_e64 v68, v68, v100
	v_mul_f32_e64 v69, v69, v100
	s_nop 0
	v_pk_mul_f32 v[134:135], v[134:135], v[100:101] op_sel_hi:[1,0]
	v_writelane_b32 v244, s91, 63
	s_waitcnt lgkmcnt(0)
	v_mfma_f32_16x16x32_bf16 v[72:75], v[54:57], v[146:149], v[72:75]
	v_mul_f32_e64 v142, v70, v70
	v_mul_f32_e64 v143, v71, v71
	v_pk_mul_f32 v[144:145], v[68:69], v[68:69]
	v_cvt_pk_bf16_f32 v68, v68, v69
	v_cvt_pk_bf16_f32 v69, v70, v71
	v_pk_mul_f32 v[70:71], v[136:137], v[100:101] op_sel_hi:[1,0]
	v_pk_mov_b32 v[146:147], v[144:145], v[142:143] op_sel:[1,0]
	v_mov_b32_e32 v145, v143
	v_pk_add_f32 v[142:143], v[146:147], v[144:145]
	v_pk_mul_f32 v[136:137], v[70:71], v[70:71]
	v_add_f32_e32 v142, v142, v143
	v_pk_mul_f32 v[144:145], v[134:135], v[134:135]
	v_cvt_pk_bf16_f32 v134, v134, v135
	v_cvt_pk_bf16_f32 v135, v70, v71
	v_pk_mul_f32 v[70:71], v[138:139], v[100:101] op_sel_hi:[1,0]
	v_add_f32_e32 v143, v110, v142
	v_pk_mov_b32 v[146:147], v[144:145], v[136:137] op_sel:[1,0]
	v_mov_b32_e32 v145, v137
	ds_write2_b64 v99, v[68:69], v[134:135] offset1:4
	v_pk_mul_f32 v[68:69], v[140:141], v[100:101] op_sel_hi:[1,0]
	v_mul_f32_e32 v110, v70, v70
	v_pk_add_f32 v[136:137], v[146:147], v[144:145]
	v_pk_fma_f32 v[134:135], v[70:71], v[70:71], v[110:111] op_sel_hi:[1,1,0]
	v_mul_f32_e32 v110, v68, v68
	v_pk_add_f32 v[136:137], v[136:137], v[136:137] op_sel_hi:[0,1]
	v_pk_fma_f32 v[138:139], v[68:69], v[68:69], v[110:111] op_sel_hi:[1,1,0]
	v_cvt_pk_bf16_f32 v70, v70, v71
	v_cvt_pk_bf16_f32 v71, v68, v69
	v_pk_mul_f32 v[68:69], v[74:75], v[100:101] op_sel_hi:[1,0]
	v_pk_mul_f32 v[72:73], v[72:73], v[100:101] op_sel_hi:[1,0]
	v_mul_f32_e32 v136, v68, v68
	v_mul_f32_e32 v134, v72, v72
	v_mul_f32_e32 v138, v73, v73
	v_mul_f32_e32 v142, v69, v69
	v_pk_add_f32 v[74:75], v[134:135], v[138:139]
	v_pk_add_f32 v[134:135], v[136:137], v[142:143]
	s_and_b64 vcc, exec, s[2:3]
	v_pk_add_f32 v[74:75], v[74:75], v[134:135]
	s_mov_b32 s90, 1
	v_add_f32_e32 v110, v74, v75
	s_mov_b64 s[2:3], 0
	v_cvt_pk_bf16_f32 v72, v72, v73
	v_cvt_pk_bf16_f32 v73, v68, v69
	ds_write2_b64 v99, v[70:71], v[72:73] offset0:8 offset1:12
	s_cbranch_vccnz .LBB0_181

.LBB0_209:
	ds_read_b128 v[172:175], v136
	ds_read_b128 v[176:179], v136 offset:64
	ds_read_b128 v[196:199], v136 offset:2304
	ds_read_b128 v[200:203], v136 offset:2368
	ds_read_b128 v[204:207], v136 offset:4672
	ds_read_b128 v[208:211], v136 offset:4608
	ds_read_b128 v[212:215], v136 offset:6912
	ds_read_b128 v[216:219], v136 offset:6976
	s_add_u32 s0, s0, 64
	s_addc_u32 s1, s1, 0
	s_waitcnt lgkmcnt(7)
	v_mfma_f32_16x16x32_bf16 v[48:51], v[172:175], v[104:107], 0
	ds_read_b128 v[220:223], v136 offset:9216
	s_add_u32 s4, s4, 0x80
	s_addc_u32 s5, s5, 0
	s_cmpk_lg_i32 s4, 0x200
	s_waitcnt lgkmcnt(6)
	v_mfma_f32_16x16x32_bf16 v[56:59], v[196:199], v[104:107], 0
	v_mfma_f32_16x16x32_bf16 v[108:111], v[176:179], v[44:47], v[48:51]
	ds_read_b128 v[172:175], v136 offset:9280
	ds_read_b128 v[196:199], v136 offset:11520
	s_nop 1
	s_waitcnt lgkmcnt(7)
	v_mfma_f32_16x16x32_bf16 v[100:103], v[200:203], v[44:47], v[56:59]
	ds_read_b128 v[176:179], v136 offset:11584
	s_nop 2
	s_waitcnt lgkmcnt(6)
	v_mfma_f32_16x16x32_bf16 v[48:51], v[208:211], v[104:107], 0
	v_mfma_f32_16x16x32_bf16 v[96:99], v[204:207], v[44:47], v[48:51]
	ds_read_b128 v[200:203], v136 offset:13824
	ds_read_b128 v[208:211], v136 offset:13888
	s_nop 6
	s_waitcnt lgkmcnt(7)
	v_mfma_f32_16x16x32_bf16 v[52:55], v[212:215], v[104:107], 0
	ds_read_b128 v[204:207], v136 offset:16128
	s_waitcnt lgkmcnt(7)
	v_mfma_f32_16x16x32_bf16 v[92:95], v[216:219], v[44:47], v[52:55]
	ds_read_b128 v[212:215], v136 offset:16192
	s_waitcnt lgkmcnt(7)
	v_mfma_f32_16x16x32_bf16 v[52:55], v[220:223], v[104:107], 0
	ds_read_b128 v[216:219], v136 offset:18432
	s_waitcnt lgkmcnt(7)
	v_mfma_f32_16x16x32_bf16 v[88:91], v[172:175], v[44:47], v[52:55]
	ds_read_b128 v[220:223], v136 offset:18496
	s_waitcnt lgkmcnt(7)
	v_mfma_f32_16x16x32_bf16 v[52:55], v[196:199], v[104:107], 0
	ds_read_b128 v[172:175], v136 offset:20736
	s_waitcnt lgkmcnt(7)
	v_mfma_f32_16x16x32_bf16 v[84:87], v[176:179], v[44:47], v[52:55]
	ds_read_b128 v[196:199], v136 offset:20800
	s_waitcnt lgkmcnt(7)
	v_mfma_f32_16x16x32_bf16 v[52:55], v[200:203], v[104:107], 0
	ds_read_b128 v[176:179], v136 offset:23040
	s_waitcnt lgkmcnt(7)
	v_mfma_f32_16x16x32_bf16 v[80:83], v[208:211], v[44:47], v[52:55]
	ds_read_b128 v[200:203], v136 offset:23104
	s_waitcnt lgkmcnt(7)
	v_mfma_f32_16x16x32_bf16 v[52:55], v[204:207], v[104:107], 0
	ds_read_b128 v[208:211], v136 offset:25344
	s_waitcnt lgkmcnt(7)
	v_mfma_f32_16x16x32_bf16 v[76:79], v[212:215], v[44:47], v[52:55]
	ds_read_b128 v[204:207], v136 offset:25408
	s_waitcnt lgkmcnt(7)
	v_mfma_f32_16x16x32_bf16 v[52:55], v[216:219], v[104:107], 0
	ds_read_b128 v[212:215], v136 offset:27648
	s_waitcnt lgkmcnt(7)
	v_mfma_f32_16x16x32_bf16 v[68:71], v[220:223], v[44:47], v[52:55]
	ds_read_b128 v[216:219], v136 offset:27712
	s_waitcnt lgkmcnt(7)
	v_mfma_f32_16x16x32_bf16 v[52:55], v[172:175], v[104:107], 0
	ds_read_b128 v[220:223], v136 offset:29952
	s_waitcnt lgkmcnt(6)
	v_mfma_f32_16x16x32_bf16 v[56:59], v[176:179], v[104:107], 0
	s_waitcnt lgkmcnt(5)
	v_mfma_f32_16x16x32_bf16 v[72:75], v[200:203], v[44:47], v[56:59]
	v_mfma_f32_16x16x32_bf16 v[64:67], v[196:199], v[44:47], v[52:55]
	ds_read_b128 v[172:175], v136 offset:30016
	ds_read_b128 v[176:179], v136 offset:32256
	ds_read_b128 v[200:203], v136 offset:32320
	s_nop 4
	v_max3_f32 v56, v108, s16, v109
	v_max3_f32 v56, v56, v110, v111
	v_max3_f32 v60, v56, v100, v101
	s_waitcnt lgkmcnt(7)
	v_mfma_f32_16x16x32_bf16 v[56:59], v[208:211], v[104:107], 0
	ds_read_b128 v[196:199], v136 offset:34560
	v_max3_f32 v60, v60, v102, v103
	v_max3_f32 v60, v60, v96, v97
	v_max3_f32 v138, v60, v98, v99
	s_waitcnt lgkmcnt(7)
	v_mfma_f32_16x16x32_bf16 v[60:63], v[204:207], v[44:47], v[56:59]
	ds_read_b128 v[208:211], v136 offset:34624
	v_max3_f32 v56, v138, v92, v93
	v_max3_f32 v56, v56, v94, v95
	v_max3_f32 v56, v56, v88, v89
	s_waitcnt lgkmcnt(7)
	v_mfma_f32_16x16x32_bf16 v[48:51], v[212:215], v[104:107], 0
	ds_read_b128 v[204:207], v240
	v_max3_f32 v56, v56, v90, v91
	v_max3_f32 v56, v56, v84, v85
	v_max3_f32 v138, v56, v86, v87
	s_waitcnt lgkmcnt(7)
	v_mfma_f32_16x16x32_bf16 v[56:59], v[216:219], v[44:47], v[48:51]
	ds_read_b128 v[212:215], v241
	s_nop 2
	v_max3_f32 v48, v138, v80, v81
	v_max3_f32 v48, v48, v82, v83
	v_max3_f32 v52, v48, v76, v77
	s_waitcnt lgkmcnt(7)
	v_mfma_f32_16x16x32_bf16 v[48:51], v[220:223], v[104:107], 0
	ds_read_b128 v[216:219], v242 offset:256
	v_max3_f32 v52, v52, v78, v79
	v_max3_f32 v52, v52, v68, v69
	v_max3_f32 v138, v52, v70, v71
	s_waitcnt lgkmcnt(7)
	v_mfma_f32_16x16x32_bf16 v[52:55], v[172:175], v[44:47], v[48:51]
	ds_read_b128 v[220:223], v245 offset:512
	s_nop 2
	v_max3_f32 v48, v138, v64, v65
	v_max3_f32 v48, v48, v66, v67
	v_max3_f32 v138, v48, v72, v73
	s_waitcnt lgkmcnt(7)
	v_mfma_f32_16x16x32_bf16 v[48:51], v[176:179], v[104:107], 0
	ds_read_b128 v[172:175], v240 offset:64
	v_max3_f32 v138, v138, v74, v75
	v_max3_f32 v138, v138, v60, v61
	v_max3_f32 v138, v138, v62, v63
	s_waitcnt lgkmcnt(6)
	v_mfma_f32_16x16x32_bf16 v[104:107], v[196:199], v[104:107], 0
	v_max3_f32 v138, v138, v56, v57
	v_max3_f32 v138, v138, v58, v59
	v_max3_f32 v138, v138, v52, v53
	v_mfma_f32_16x16x32_bf16 v[48:51], v[200:203], v[44:47], v[48:51]
	ds_read_b128 v[176:179], v242 offset:320
	ds_read_b128 v[196:199], v241 offset:64
	v_max3_f32 v138, v138, v54, v55
	s_waitcnt lgkmcnt(7)
	v_mfma_f32_16x16x32_bf16 v[44:47], v[208:211], v[44:47], v[104:107]
	ds_read_b128 v[200:203], v245 offset:576
	s_nop 4
	v_max3_f32 v138, v138, v48, v49
	v_max3_f32 v138, v138, v50, v51
	s_nop 0
	v_max3_f32 v104, v138, v44, v45
	v_max3_f32 v104, v104, v46, v47
	v_mov_b32_e32 v105, v104
	s_nop 1
	v_permlane16_swap_b32 v105, v104
	s_nop 0
	v_max_f32_e32 v105, v105, v105
	v_max_f32_e32 v104, v104, v105
	v_mov_b32_e32 v105, v104
	s_nop 1
	v_permlane32_swap_b32 v105, v104
	s_nop 0
	v_max_f32_e32 v105, v105, v105
	v_max_f32_e32 v104, v104, v105
	v_sub_f32_e32 v105, v108, v104
	v_exp_f32_e32 v106, v105
	v_sub_f32_e32 v105, v109, v104
	v_exp_f32_e32 v107, v105
	v_sub_f32_e32 v105, v110, v104
	v_exp_f32_e32 v108, v105
	v_sub_f32_e32 v105, v111, v104
	v_exp_f32_e32 v110, v105
	v_sub_f32_e32 v100, v100, v104
	v_add_f32_e32 v105, 0, v106
	v_exp_f32_e32 v109, v100
	v_sub_f32_e32 v100, v101, v104
	v_add_f32_e32 v105, v107, v105
	v_exp_f32_e32 v111, v100
	v_sub_f32_e32 v100, v102, v104
	v_add_f32_e32 v105, v108, v105
	v_exp_f32_e32 v138, v100
	v_sub_f32_e32 v100, v103, v104
	v_add_f32_e32 v105, v110, v105
	v_exp_f32_e32 v139, v100
	v_add_f32_e32 v100, v109, v105
	v_add_f32_e32 v100, v111, v100
	v_add_f32_e32 v100, v138, v100
	v_sub_f32_e32 v96, v96, v104
	v_add_f32_e32 v102, v139, v100
	v_exp_f32_e32 v100, v96
	v_sub_f32_e32 v96, v97, v104
	v_exp_f32_e32 v101, v96
	v_sub_f32_e32 v96, v98, v104
	v_exp_f32_e32 v97, v96
	v_sub_f32_e32 v96, v99, v104
	v_exp_f32_e32 v98, v96
	v_sub_f32_e32 v92, v92, v104
	v_add_f32_e32 v96, v100, v102
	v_exp_f32_e32 v99, v92
	v_sub_f32_e32 v92, v93, v104
	v_add_f32_e32 v96, v101, v96
	v_exp_f32_e32 v102, v92
	v_sub_f32_e32 v92, v94, v104
	v_add_f32_e32 v96, v97, v96
	v_exp_f32_e32 v103, v92
	v_sub_f32_e32 v92, v95, v104
	v_add_f32_e32 v96, v98, v96
	v_exp_f32_e32 v105, v92
	v_add_f32_e32 v92, v99, v96
	v_add_f32_e32 v92, v102, v92
	v_add_f32_e32 v92, v103, v92
	v_sub_f32_e32 v88, v88, v104
	v_add_f32_e32 v94, v105, v92
	v_exp_f32_e32 v92, v88
	v_sub_f32_e32 v88, v89, v104
	v_exp_f32_e32 v93, v88
	v_sub_f32_e32 v88, v90, v104
	v_exp_f32_e32 v89, v88
	v_sub_f32_e32 v88, v91, v104
	v_exp_f32_e32 v90, v88
	v_sub_f32_e32 v84, v84, v104
	v_add_f32_e32 v88, v92, v94
	v_exp_f32_e32 v91, v84
	v_sub_f32_e32 v84, v85, v104
	v_add_f32_e32 v88, v93, v88
	v_exp_f32_e32 v94, v84
	v_sub_f32_e32 v84, v86, v104
	v_add_f32_e32 v88, v89, v88
	v_exp_f32_e32 v95, v84
	v_sub_f32_e32 v84, v87, v104
	v_add_f32_e32 v88, v90, v88
	v_exp_f32_e32 v96, v84
	v_add_f32_e32 v84, v91, v88
	v_add_f32_e32 v84, v94, v84
	v_add_f32_e32 v84, v95, v84
	v_sub_f32_e32 v80, v80, v104
	v_add_f32_e32 v86, v96, v84
	v_exp_f32_e32 v84, v80
	v_sub_f32_e32 v80, v81, v104
	v_exp_f32_e32 v85, v80
	v_sub_f32_e32 v80, v82, v104
	v_exp_f32_e32 v81, v80
	v_sub_f32_e32 v80, v83, v104
	v_exp_f32_e32 v82, v80
	v_sub_f32_e32 v76, v76, v104
	v_add_f32_e32 v80, v84, v86
	v_exp_f32_e32 v83, v76
	v_sub_f32_e32 v76, v77, v104
	v_add_f32_e32 v80, v85, v80
	v_exp_f32_e32 v86, v76
	v_sub_f32_e32 v76, v78, v104
	v_add_f32_e32 v80, v81, v80
	v_exp_f32_e32 v87, v76
	v_sub_f32_e32 v76, v79, v104
	v_add_f32_e32 v80, v82, v80
	v_exp_f32_e32 v88, v76
	v_add_f32_e32 v76, v83, v80
	v_add_f32_e32 v76, v86, v76
	v_add_f32_e32 v76, v87, v76
	v_sub_f32_e32 v68, v68, v104
	v_add_f32_e32 v78, v88, v76
	v_exp_f32_e32 v76, v68
	v_sub_f32_e32 v68, v69, v104
	v_exp_f32_e32 v77, v68
	v_sub_f32_e32 v68, v70, v104
	v_exp_f32_e32 v68, v68
	v_sub_f32_e32 v69, v71, v104
	v_exp_f32_e32 v69, v69
	v_sub_f32_e32 v64, v64, v104
	v_add_f32_e32 v70, v76, v78
	v_exp_f32_e32 v71, v64
	v_sub_f32_e32 v64, v65, v104
	v_add_f32_e32 v70, v77, v70
	v_exp_f32_e32 v78, v64
	v_sub_f32_e32 v64, v66, v104
	v_add_f32_e32 v70, v68, v70
	v_exp_f32_e32 v79, v64
	v_sub_f32_e32 v64, v67, v104
	v_add_f32_e32 v70, v69, v70
	v_exp_f32_e32 v80, v64
	v_add_f32_e32 v64, v71, v70
	v_add_f32_e32 v64, v78, v64
	v_add_f32_e32 v64, v79, v64
	v_add_f32_e32 v70, v80, v64
	v_sub_f32_e32 v64, v72, v104
	v_exp_f32_e32 v65, v64
	v_sub_f32_e32 v64, v73, v104
	v_exp_f32_e32 v67, v64
	v_sub_f32_e32 v64, v74, v104
	v_exp_f32_e32 v64, v64
	v_sub_f32_e32 v66, v75, v104
	v_exp_f32_e32 v66, v66
	v_sub_f32_e32 v60, v60, v104
	v_add_f32_e32 v70, v65, v70
	v_exp_f32_e32 v60, v60
	v_sub_f32_e32 v61, v61, v104
	v_add_f32_e32 v70, v67, v70
	v_exp_f32_e32 v61, v61
	v_sub_f32_e32 v62, v62, v104
	v_add_f32_e32 v70, v64, v70
	v_exp_f32_e32 v62, v62
	v_sub_f32_e32 v63, v63, v104
	v_add_f32_e32 v70, v66, v70
	v_exp_f32_e32 v63, v63
	v_add_f32_e32 v70, v60, v70
	v_add_f32_e32 v70, v61, v70
	v_add_f32_e32 v70, v62, v70
	v_add_f32_e32 v75, v63, v70
	v_sub_f32_e32 v56, v56, v104
	v_add_u32_e32 v70, v133, v115
	v_add_u32_e32 v73, 0x9000, v70
	v_add_u32_e32 v72, 0x9000, v137
	v_add_u32_e32 v70, 0xb000, v137
	v_exp_f32_e32 v74, v56
	v_add_u32_e32 v56, 0xd000, v137
	v_cvt_pk_bf16_f32 v106, v106, v107
	v_cvt_pk_bf16_f32 v107, v108, v110
	v_cvt_pk_bf16_f32 v108, v109, v111
	v_cvt_pk_bf16_f32 v109, v138, v139
	s_waitcnt lgkmcnt(7)
	s_nop 0
	v_mfma_f32_16x16x32_bf16 v[138:141], v[204:207], v[106:109], 0
	ds_read_b128 v[208:211], v240 offset:128
	v_cvt_pk_bf16_f32 v100, v100, v101
	v_cvt_pk_bf16_f32 v101, v97, v98
	v_cvt_pk_bf16_f32 v102, v99, v102
	s_waitcnt lgkmcnt(7)
	v_mfma_f32_16x16x32_bf16 v[142:145], v[212:215], v[106:109], 0
	ds_read_b128 v[204:207], v242 offset:384
	v_cvt_pk_bf16_f32 v103, v103, v105
	v_cvt_pk_bf16_f32 v92, v92, v93
	s_waitcnt lgkmcnt(7)
	v_mfma_f32_16x16x32_bf16 v[146:149], v[216:219], v[106:109], 0
	ds_read_b128 v[212:215], v241 offset:128
	v_cvt_pk_bf16_f32 v93, v89, v90
	v_cvt_pk_bf16_f32 v94, v91, v94
	v_cvt_pk_bf16_f32 v95, v95, v96
	s_waitcnt lgkmcnt(7)
	v_mfma_f32_16x16x32_bf16 v[106:109], v[220:223], v[106:109], 0
	ds_read_b128 v[216:219], v245 offset:640
	v_cvt_pk_bf16_f32 v84, v84, v85
	v_cvt_pk_bf16_f32 v85, v81, v82
	s_waitcnt lgkmcnt(7)
	v_mfma_f32_16x16x32_bf16 v[138:141], v[172:175], v[100:103], v[138:141]
	ds_read_b128 v[220:223], v240 offset:192
	v_cvt_pk_bf16_f32 v86, v83, v86
	v_cvt_pk_bf16_f32 v87, v87, v88
	s_waitcnt lgkmcnt(6)
	v_mfma_f32_16x16x32_bf16 v[142:145], v[196:199], v[100:103], v[142:145]
	v_sub_f32_e32 v57, v57, v104
	v_cvt_pk_bf16_f32 v76, v76, v77
	v_mfma_f32_16x16x32_bf16 v[146:149], v[176:179], v[100:103], v[146:149]
	ds_read_b128 v[172:175], v241 offset:192
	ds_read_b128 v[196:199], v242 offset:448
	v_cvt_pk_bf16_f32 v77, v68, v69
	v_cvt_pk_bf16_f32 v78, v71, v78
	v_cvt_pk_bf16_f32 v79, v79, v80
	s_waitcnt lgkmcnt(7)
	v_mfma_f32_16x16x32_bf16 v[98:101], v[200:203], v[100:103], v[106:109]
	ds_read_b128 v[176:179], v245 offset:704
	v_exp_f32_e32 v57, v57
	v_sub_f32_e32 v58, v58, v104
	s_waitcnt lgkmcnt(7)
	v_mfma_f32_16x16x32_bf16 v[138:141], v[208:211], v[92:95], v[138:141]
	ds_read_b128 v[200:203], v240 offset:256
	v_exp_f32_e32 v58, v58
	v_sub_f32_e32 v59, v59, v104
	s_waitcnt lgkmcnt(6)
	v_mfma_f32_16x16x32_bf16 v[106:109], v[212:215], v[92:95], v[142:145]
	v_exp_f32_e32 v59, v59
	v_sub_f32_e32 v52, v52, v104
	v_add_f32_e32 v75, v74, v75
	v_mfma_f32_16x16x32_bf16 v[142:145], v[204:207], v[92:95], v[146:149]
	ds_read_b128 v[208:211], v241 offset:256
	ds_read_b128 v[212:215], v242 offset:512
	v_exp_f32_e32 v52, v52
	v_sub_f32_e32 v53, v53, v104
	v_add_f32_e32 v75, v57, v75
	s_waitcnt lgkmcnt(7)
	v_mfma_f32_16x16x32_bf16 v[90:93], v[216:219], v[92:95], v[98:101]
	ds_read_b128 v[204:207], v245 offset:768
	v_exp_f32_e32 v53, v53
	v_sub_f32_e32 v54, v54, v104
	s_waitcnt lgkmcnt(7)
	v_mfma_f32_16x16x32_bf16 v[138:141], v[220:223], v[84:87], v[138:141]
	ds_read_b128 v[216:219], v241 offset:320
	v_add_f32_e32 v75, v58, v75
	v_exp_f32_e32 v54, v54
	s_waitcnt lgkmcnt(7)
	v_mfma_f32_16x16x32_bf16 v[94:97], v[172:175], v[84:87], v[106:109]
	ds_read_b128 v[220:223], v245 offset:832
	v_sub_f32_e32 v55, v55, v104
	v_add_f32_e32 v75, v59, v75
	v_exp_f32_e32 v55, v55
	s_waitcnt lgkmcnt(7)
	v_mfma_f32_16x16x32_bf16 v[98:101], v[196:199], v[84:87], v[142:145]
	ds_read_b128 v[172:175], v242 offset:576
	v_sub_f32_e32 v48, v48, v104
	v_add_f32_e32 v75, v52, v75
	v_exp_f32_e32 v102, v48
	s_waitcnt lgkmcnt(7)
	v_mfma_f32_16x16x32_bf16 v[82:85], v[176:179], v[84:87], v[90:93]
	ds_read_b128 v[196:199], v240 offset:320
	v_sub_f32_e32 v48, v49, v104
	v_add_f32_e32 v75, v53, v75
	s_waitcnt lgkmcnt(7)
	v_mfma_f32_16x16x32_bf16 v[106:109], v[200:203], v[76:79], v[138:141]
	ds_read_b128 v[176:179], v240 offset:384
	v_exp_f32_e32 v103, v48
	v_sub_f32_e32 v48, v50, v104
	v_add_f32_e32 v75, v54, v75
	s_waitcnt lgkmcnt(7)
	v_mfma_f32_16x16x32_bf16 v[86:89], v[208:211], v[76:79], v[94:97]
	ds_read_b128 v[200:203], v242 offset:640
	v_exp_f32_e32 v68, v48
	v_add_f32_e32 v75, v55, v75
	v_cvt_pk_bf16_f32 v80, v65, v67
	s_waitcnt lgkmcnt(7)
	v_mfma_f32_16x16x32_bf16 v[90:93], v[212:215], v[76:79], v[98:101]
	ds_read_b128 v[208:211], v241 offset:384
	v_cvt_pk_bf16_f32 v81, v64, v66
	s_waitcnt lgkmcnt(7)
	v_mfma_f32_16x16x32_bf16 v[76:79], v[204:207], v[76:79], v[82:85]
	ds_read_b128 v[212:215], v245 offset:896
	v_cvt_pk_bf16_f32 v82, v60, v61
	v_cvt_pk_bf16_f32 v83, v62, v63
	v_add_f32_e32 v48, v102, v75
	v_add_f32_e32 v48, v103, v48
	v_add_f32_e32 v69, v68, v48
	v_sub_f32_e32 v71, v51, v104
	s_waitcnt lgkmcnt(7)
	v_mfma_f32_16x16x32_bf16 v[84:87], v[216:219], v[80:83], v[86:89]
	ds_read_b128 v[204:207], v240 offset:448
	v_exp_f32_e32 v71, v71
	v_sub_f32_e32 v44, v44, v104
	v_exp_f32_e32 v94, v44
	s_waitcnt lgkmcnt(6)
	v_mfma_f32_16x16x32_bf16 v[60:63], v[172:175], v[80:83], v[90:93]
	v_sub_f32_e32 v44, v45, v104
	v_exp_f32_e32 v95, v44
	v_sub_f32_e32 v45, v46, v104
	v_mfma_f32_16x16x32_bf16 v[64:67], v[220:223], v[80:83], v[76:79]
	ds_read_b128 v[216:219], v241 offset:448
	ds_read_b128 v[172:175], v242 offset:704
	v_cvt_pk_bf16_f32 v76, v52, v53
	v_cvt_pk_bf16_f32 v77, v54, v55
	s_waitcnt lgkmcnt(7)
	v_mfma_f32_16x16x32_bf16 v[48:51], v[196:199], v[80:83], v[106:109]
	ds_read_b128 v[220:223], v245 offset:960
	v_add_f32_e32 v69, v71, v69
	v_cvt_pk_bf16_f32 v74, v74, v57
	v_exp_f32_e32 v57, v45
	v_sub_f32_e32 v45, v47, v104
	v_add_f32_e32 v44, v94, v69
	v_exp_f32_e32 v69, v45
	v_add_f32_e32 v44, v95, v44
	v_cvt_pk_bf16_f32 v75, v58, v59
	s_nop 0
	v_add_f32_e32 v58, v57, v44
	s_waitcnt lgkmcnt(7)
	v_mfma_f32_16x16x32_bf16 v[48:51], v[176:179], v[74:77], v[48:51]
	s_waitcnt lgkmcnt(6)
	v_mfma_f32_16x16x32_bf16 v[44:47], v[200:203], v[74:77], v[60:63]
	v_add_f32_e32 v73, v69, v58
	v_mov_b32_e32 v82, v73
	s_nop 1
	v_permlane16_swap_b32 v82, v73
	v_cvt_pk_bf16_f32 v69, v57, v69
	s_waitcnt lgkmcnt(5)
	v_mfma_f32_16x16x32_bf16 v[78:81], v[208:211], v[74:77], v[84:87]
	v_add_f32_e32 v57, v73, v82
	s_waitcnt lgkmcnt(4)
	v_mfma_f32_16x16x32_bf16 v[58:61], v[212:215], v[74:77], v[64:67]
	v_mov_b32_e32 v74, v57
	s_nop 1
	v_permlane32_swap_b32 v74, v57
	v_cvt_pk_bf16_f32 v66, v102, v103
	v_cvt_pk_bf16_f32 v67, v68, v71
	v_cvt_pk_bf16_f32 v68, v94, v95
	s_nop 0
	s_waitcnt lgkmcnt(3)
	v_mfma_f32_16x16x32_bf16 v[48:51], v[204:207], v[66:69], v[48:51]
	v_add_f32_e32 v56, v57, v74
	v_rcp_f32_e32 v56, v56
	s_waitcnt lgkmcnt(2)
	v_mfma_f32_16x16x32_bf16 v[62:65], v[216:219], v[66:69], v[78:81]
	s_nop 3
	v_mul_f32_e64 v50, v56, v50
	v_mul_f32_e64 v51, v56, v51
	v_pk_mul_f32 v[48:49], v[56:57], v[48:49] op_sel_hi:[0,1]
	s_waitcnt lgkmcnt(1)
	v_mfma_f32_16x16x32_bf16 v[44:47], v[172:175], v[66:69], v[44:47]
	s_waitcnt lgkmcnt(0)
	v_mfma_f32_16x16x32_bf16 v[52:55], v[220:223], v[66:69], v[58:61]
	s_nop 2
	v_mul_f32_e64 v58, v50, v50
	v_mul_f32_e64 v59, v51, v51
	v_pk_mul_f32 v[60:61], v[48:49], v[48:49]
	v_cvt_pk_bf16_f32 v48, v48, v49
	v_cvt_pk_bf16_f32 v49, v50, v51
	s_nop 0
	v_pk_mov_b32 v[66:67], v[60:61], v[58:59] op_sel:[1,0]
	v_mov_b32_e32 v61, v59
	v_pk_add_f32 v[58:59], v[66:67], v[60:61]
	s_nop 0
	v_add_f32_e32 v57, v58, v59
	v_pk_mul_f32 v[50:51], v[56:57], v[64:65] op_sel_hi:[0,1]
	v_pk_mul_f32 v[60:61], v[56:57], v[62:63] op_sel_hi:[0,1]
	v_pk_mul_f32 v[62:63], v[50:51], v[50:51]
	v_pk_mul_f32 v[64:65], v[60:61], v[60:61]
	v_pk_mul_f32 v[52:53], v[56:57], v[52:53] op_sel_hi:[0,1]
	v_pk_mov_b32 v[66:67], v[64:65], v[62:63] op_sel:[1,0]
	v_mov_b32_e32 v65, v63
	v_pk_add_f32 v[62:63], v[66:67], v[64:65]
	v_cvt_pk_bf16_f32 v60, v60, v61
	v_cvt_pk_bf16_f32 v61, v50, v51
	v_pk_mul_f32 v[46:47], v[56:57], v[46:47] op_sel_hi:[0,1]
	v_pk_mul_f32 v[44:45], v[56:57], v[44:45] op_sel_hi:[0,1]
	v_pk_mul_f32 v[50:51], v[56:57], v[54:55] op_sel_hi:[0,1]
	v_mul_f32_e32 v56, v53, v53
	v_pk_add_f32 v[54:55], v[62:63], v[62:63] op_sel:[0,1] op_sel_hi:[1,0]
	v_add_f32_e32 v58, v130, v57
	v_mul_f32_e32 v57, v50, v50
	v_mov_b32_e32 v55, v56
	v_mul_f32_e32 v56, v45, v45
	ds_write2_b64 v134, v[48:49], v[60:61] offset1:4
	v_cvt_pk_bf16_f32 v48, v44, v45
	v_pk_fma_f32 v[44:45], v[44:45], v[44:45], v[56:57] op_sel_hi:[1,1,0]
	v_mul_f32_e32 v56, v47, v47
	v_cvt_pk_bf16_f32 v49, v46, v47
	v_mul_f32_e32 v60, v51, v51
	v_pk_fma_f32 v[46:47], v[46:47], v[46:47], v[56:57] op_sel_hi:[1,1,0]
	v_mul_f32_e32 v59, v52, v52
	v_mov_b32_e32 v45, v57
	v_mov_b32_e32 v47, v60
	v_pk_add_f32 v[54:55], v[58:59], v[54:55]
	v_pk_add_f32 v[44:45], v[44:45], v[46:47]
	s_nop 0
	v_pk_add_f32 v[44:45], v[54:55], v[44:45]
	s_nop 0
	v_add_f32_e32 v130, v44, v45
	v_cvt_pk_bf16_f32 v44, v52, v53
	v_cvt_pk_bf16_f32 v45, v50, v51
	ds_write2_b64 v134, v[48:49], v[44:45] offset0:8 offset1:12
	v_add_u32_e32 v134, 0x80, v134
	s_cbranch_scc0 .LBB0_215
